# fin2 + spatial W-hoist + LN-stats batched 4 rows (alignment-preserving pad)
# speedup vs baseline: 1.0132x; 1.0011x over previous
.Lln_batch:
	s_mov_b64 s[6:7], 0x1000
	v_lshl_add_u64 v[232:233], v[0:1], 0, s[6:7]
	v_lshl_add_u64 v[234:235], v[232:233], 0, s[6:7]
	v_lshl_add_u64 v[236:237], v[234:235], 0, s[6:7]
	global_load_dwordx4 v[200:203], v[0:1], off
	global_load_dwordx4 v[204:207], v[0:1], off offset:16
	global_load_dwordx4 v[208:211], v[232:233], off
	global_load_dwordx4 v[212:215], v[232:233], off offset:16
	global_load_dwordx4 v[216:219], v[234:235], off
	global_load_dwordx4 v[220:223], v[234:235], off offset:16
	global_load_dwordx4 v[224:227], v[236:237], off
	global_load_dwordx4 v[228:231], v[236:237], off offset:16
	s_waitcnt vmcnt(7)
	v_lshlrev_b32_e32 v10, 16, v200
	v_and_b32_e32 v11, 0xffff0000, v200
	v_add_f32_e32 v200, 0, v10
	v_lshlrev_b32_e32 v13, 16, v201
	v_add_f32_e32 v200, v200, v11
	v_and_b32_e32 v201, 0xffff0000, v201
	v_add_f32_e32 v200, v200, v13
	v_lshlrev_b32_e32 v15, 16, v202
	v_add_f32_e32 v200, v200, v201
	v_and_b32_e32 v202, 0xffff0000, v202
	v_add_f32_e32 v200, v200, v15
	v_lshlrev_b32_e32 v17, 16, v203
	v_add_f32_e32 v200, v200, v202
	v_and_b32_e32 v203, 0xffff0000, v203
	v_add_f32_e32 v200, v200, v17
	s_waitcnt vmcnt(6)
	v_lshlrev_b32_e32 v12, 16, v204
	v_add_f32_e32 v200, v200, v203
	v_and_b32_e32 v204, 0xffff0000, v204
	v_add_f32_e32 v200, v200, v12
	v_lshlrev_b32_e32 v14, 16, v205
	v_add_f32_e32 v200, v200, v204
	v_and_b32_e32 v205, 0xffff0000, v205
	v_add_f32_e32 v200, v200, v14
	v_lshlrev_b32_e32 v16, 16, v206
	v_add_f32_e32 v200, v200, v205
	v_and_b32_e32 v206, 0xffff0000, v206
	v_add_f32_e32 v200, v200, v16
	v_lshlrev_b32_e32 v18, 16, v207
	v_add_f32_e32 v200, v200, v206
	v_and_b32_e32 v207, 0xffff0000, v207
	v_add_f32_e32 v200, v200, v18
	v_add_f32_e32 v200, v200, v207
	ds_swizzle_b32 v19, v200 offset:swizzle(SWAP,16)
	s_waitcnt lgkmcnt(0)
	v_add_f32_e32 v200, v200, v19
	ds_swizzle_b32 v19, v200 offset:swizzle(SWAP,8)
	s_waitcnt lgkmcnt(0)
	v_add_f32_e32 v200, v200, v19
	ds_swizzle_b32 v19, v200 offset:swizzle(SWAP,4)
	s_waitcnt lgkmcnt(0)
	v_add_f32_e32 v200, v200, v19
	ds_swizzle_b32 v19, v200 offset:swizzle(SWAP,2)
	s_waitcnt lgkmcnt(0)
	v_add_f32_e32 v200, v200, v19
	ds_swizzle_b32 v19, v200 offset:swizzle(SWAP,1)
	s_waitcnt lgkmcnt(0)
	v_add_f32_e32 v200, v200, v19
	v_mov_b32_e32 v19, v200
	s_nop 1
	v_permlane32_swap_b32_e32 v200, v19
	v_add_f32_e32 v200, v200, v19
	v_fmac_f32_e32 v11, 0xba800000, v200
	v_fmac_f32_e32 v10, 0xba800000, v200
	v_mul_f32_e32 v11, v11, v11
	v_fmac_f32_e32 v13, 0xba800000, v200
	v_fmac_f32_e32 v11, v10, v10
	v_fmac_f32_e32 v201, 0xba800000, v200
	v_fmac_f32_e32 v11, v13, v13
	v_fmac_f32_e32 v15, 0xba800000, v200
	v_fmac_f32_e32 v11, v201, v201
	v_fmac_f32_e32 v202, 0xba800000, v200
	v_fmac_f32_e32 v11, v15, v15
	v_fmac_f32_e32 v17, 0xba800000, v200
	v_fmac_f32_e32 v11, v202, v202
	v_fmac_f32_e32 v203, 0xba800000, v200
	v_fmac_f32_e32 v11, v17, v17
	v_fmac_f32_e32 v12, 0xba800000, v200
	v_fmac_f32_e32 v11, v203, v203
	v_fmac_f32_e32 v204, 0xba800000, v200
	v_fmac_f32_e32 v11, v12, v12
	v_fmac_f32_e32 v14, 0xba800000, v200
	v_fmac_f32_e32 v11, v204, v204
	v_fmac_f32_e32 v205, 0xba800000, v200
	v_fmac_f32_e32 v11, v14, v14
	v_fmac_f32_e32 v16, 0xba800000, v200
	v_fmac_f32_e32 v11, v205, v205
	v_fmac_f32_e32 v206, 0xba800000, v200
	v_fmac_f32_e32 v11, v16, v16
	v_fmac_f32_e32 v18, 0xba800000, v200
	v_fmac_f32_e32 v11, v206, v206
	v_fmac_f32_e32 v207, 0xba800000, v200
	v_fmac_f32_e32 v11, v18, v18
	v_fmac_f32_e32 v11, v207, v207
	ds_swizzle_b32 v201, v11 offset:swizzle(SWAP,16)
	s_waitcnt lgkmcnt(0)
	v_add_f32_e32 v201, v11, v201
	ds_swizzle_b32 v202, v201 offset:swizzle(SWAP,8)
	s_waitcnt lgkmcnt(0)
	v_add_f32_e32 v201, v201, v202
	ds_swizzle_b32 v202, v201 offset:swizzle(SWAP,4)
	s_waitcnt lgkmcnt(0)
	v_add_f32_e32 v201, v201, v202
	ds_swizzle_b32 v202, v201 offset:swizzle(SWAP,2)
	s_waitcnt lgkmcnt(0)
	v_add_f32_e32 v201, v201, v202
	ds_swizzle_b32 v202, v201 offset:swizzle(SWAP,1)
	s_waitcnt lgkmcnt(0)
	v_add_f32_e32 v201, v201, v202
	v_mov_b32_e32 v202, v201
	s_nop 1
	v_permlane32_swap_b32_e32 v201, v202
	s_and_saveexec_b64 s[6:7], vcc
	s_cbranch_execz .Lln_skip_0
	v_add_f32_e32 v201, v201, v202
	v_fmamk_f32 v201, v201, 0x3a800000, v169
	v_mul_f32_e32 v202, 0x4b800000, v201
	v_cmp_gt_f32_e64 s[40:41], s85, v201
	v_mul_f32_e32 v200, 0x3a800000, v200
	s_nop 0
	v_cndmask_b32_e64 v201, v201, v202, s[40:41]
	v_rsq_f32_e32 v201, v201
	v_add_u32_e32 v202, s0, v33
	v_add_u32_e32 v203, 0x11000, v202
	ds_write_b32 v203, v200
	v_mul_f32_e32 v200, 0x45800000, v201
	v_cndmask_b32_e64 v200, v201, v200, s[40:41]
	v_add_u32_e32 v201, 0x11200, v202
	ds_write_b32 v201, v200
.Lln_skip_0:
	s_or_b64 exec, exec, s[6:7]
	s_add_i32 s0, s0, 4
	s_waitcnt vmcnt(5)
	v_lshlrev_b32_e32 v10, 16, v208
	v_and_b32_e32 v11, 0xffff0000, v208
	v_add_f32_e32 v208, 0, v10
	v_lshlrev_b32_e32 v13, 16, v209
	v_add_f32_e32 v208, v208, v11
	v_and_b32_e32 v209, 0xffff0000, v209
	v_add_f32_e32 v208, v208, v13
	v_lshlrev_b32_e32 v15, 16, v210
	v_add_f32_e32 v208, v208, v209
	v_and_b32_e32 v210, 0xffff0000, v210
	v_add_f32_e32 v208, v208, v15
	v_lshlrev_b32_e32 v17, 16, v211
	v_add_f32_e32 v208, v208, v210
	v_and_b32_e32 v211, 0xffff0000, v211
	v_add_f32_e32 v208, v208, v17
	s_waitcnt vmcnt(4)
	v_lshlrev_b32_e32 v12, 16, v212
	v_add_f32_e32 v208, v208, v211
	v_and_b32_e32 v212, 0xffff0000, v212
	v_add_f32_e32 v208, v208, v12
	v_lshlrev_b32_e32 v14, 16, v213
	v_add_f32_e32 v208, v208, v212
	v_and_b32_e32 v213, 0xffff0000, v213
	v_add_f32_e32 v208, v208, v14
	v_lshlrev_b32_e32 v16, 16, v214
	v_add_f32_e32 v208, v208, v213
	v_and_b32_e32 v214, 0xffff0000, v214
	v_add_f32_e32 v208, v208, v16
	v_lshlrev_b32_e32 v18, 16, v215
	v_add_f32_e32 v208, v208, v214
	v_and_b32_e32 v215, 0xffff0000, v215
	v_add_f32_e32 v208, v208, v18
	v_add_f32_e32 v208, v208, v215
	ds_swizzle_b32 v19, v208 offset:swizzle(SWAP,16)
	s_waitcnt lgkmcnt(0)
	v_add_f32_e32 v208, v208, v19
	ds_swizzle_b32 v19, v208 offset:swizzle(SWAP,8)
	s_waitcnt lgkmcnt(0)
	v_add_f32_e32 v208, v208, v19
	ds_swizzle_b32 v19, v208 offset:swizzle(SWAP,4)
	s_waitcnt lgkmcnt(0)
	v_add_f32_e32 v208, v208, v19
	ds_swizzle_b32 v19, v208 offset:swizzle(SWAP,2)
	s_waitcnt lgkmcnt(0)
	v_add_f32_e32 v208, v208, v19
	ds_swizzle_b32 v19, v208 offset:swizzle(SWAP,1)
	s_waitcnt lgkmcnt(0)
	v_add_f32_e32 v208, v208, v19
	v_mov_b32_e32 v19, v208
	s_nop 1
	v_permlane32_swap_b32_e32 v208, v19
	v_add_f32_e32 v208, v208, v19
	v_fmac_f32_e32 v11, 0xba800000, v208
	v_fmac_f32_e32 v10, 0xba800000, v208
	v_mul_f32_e32 v11, v11, v11
	v_fmac_f32_e32 v13, 0xba800000, v208
	v_fmac_f32_e32 v11, v10, v10
	v_fmac_f32_e32 v209, 0xba800000, v208
	v_fmac_f32_e32 v11, v13, v13
	v_fmac_f32_e32 v15, 0xba800000, v208
	v_fmac_f32_e32 v11, v209, v209
	v_fmac_f32_e32 v210, 0xba800000, v208
	v_fmac_f32_e32 v11, v15, v15
	v_fmac_f32_e32 v17, 0xba800000, v208
	v_fmac_f32_e32 v11, v210, v210
	v_fmac_f32_e32 v211, 0xba800000, v208
	v_fmac_f32_e32 v11, v17, v17
	v_fmac_f32_e32 v12, 0xba800000, v208
	v_fmac_f32_e32 v11, v211, v211
	v_fmac_f32_e32 v212, 0xba800000, v208
	v_fmac_f32_e32 v11, v12, v12
	v_fmac_f32_e32 v14, 0xba800000, v208
	v_fmac_f32_e32 v11, v212, v212
	v_fmac_f32_e32 v213, 0xba800000, v208
	v_fmac_f32_e32 v11, v14, v14
	v_fmac_f32_e32 v16, 0xba800000, v208
	v_fmac_f32_e32 v11, v213, v213
	v_fmac_f32_e32 v214, 0xba800000, v208
	v_fmac_f32_e32 v11, v16, v16
	v_fmac_f32_e32 v18, 0xba800000, v208
	v_fmac_f32_e32 v11, v214, v214
	v_fmac_f32_e32 v215, 0xba800000, v208
	v_fmac_f32_e32 v11, v18, v18
	v_fmac_f32_e32 v11, v215, v215
	ds_swizzle_b32 v209, v11 offset:swizzle(SWAP,16)
	s_waitcnt lgkmcnt(0)
	v_add_f32_e32 v209, v11, v209
	ds_swizzle_b32 v210, v209 offset:swizzle(SWAP,8)
	s_waitcnt lgkmcnt(0)
	v_add_f32_e32 v209, v209, v210
	ds_swizzle_b32 v210, v209 offset:swizzle(SWAP,4)
	s_waitcnt lgkmcnt(0)
	v_add_f32_e32 v209, v209, v210
	ds_swizzle_b32 v210, v209 offset:swizzle(SWAP,2)
	s_waitcnt lgkmcnt(0)
	v_add_f32_e32 v209, v209, v210
	ds_swizzle_b32 v210, v209 offset:swizzle(SWAP,1)
	s_waitcnt lgkmcnt(0)
	v_add_f32_e32 v209, v209, v210
	v_mov_b32_e32 v210, v209
	s_nop 1
	v_permlane32_swap_b32_e32 v209, v210
	s_and_saveexec_b64 s[6:7], vcc
	s_cbranch_execz .Lln_skip_1
	v_add_f32_e32 v209, v209, v210
	v_fmamk_f32 v209, v209, 0x3a800000, v169
	v_mul_f32_e32 v210, 0x4b800000, v209
	v_cmp_gt_f32_e64 s[40:41], s85, v209
	v_mul_f32_e32 v208, 0x3a800000, v208
	s_nop 0
	v_cndmask_b32_e64 v209, v209, v210, s[40:41]
	v_rsq_f32_e32 v209, v209
	v_add_u32_e32 v210, s0, v33
	v_add_u32_e32 v211, 0x11000, v210
	ds_write_b32 v211, v208
	v_mul_f32_e32 v208, 0x45800000, v209
	v_cndmask_b32_e64 v208, v209, v208, s[40:41]
	v_add_u32_e32 v209, 0x11200, v210
	ds_write_b32 v209, v208
.Lln_skip_1:
	s_or_b64 exec, exec, s[6:7]
	s_add_i32 s0, s0, 4
	s_waitcnt vmcnt(3)
	v_lshlrev_b32_e32 v10, 16, v216
	v_and_b32_e32 v11, 0xffff0000, v216
	v_add_f32_e32 v216, 0, v10
	v_lshlrev_b32_e32 v13, 16, v217
	v_add_f32_e32 v216, v216, v11
	v_and_b32_e32 v217, 0xffff0000, v217
	v_add_f32_e32 v216, v216, v13
	v_lshlrev_b32_e32 v15, 16, v218
	v_add_f32_e32 v216, v216, v217
	v_and_b32_e32 v218, 0xffff0000, v218
	v_add_f32_e32 v216, v216, v15
	v_lshlrev_b32_e32 v17, 16, v219
	v_add_f32_e32 v216, v216, v218
	v_and_b32_e32 v219, 0xffff0000, v219
	v_add_f32_e32 v216, v216, v17
	s_waitcnt vmcnt(2)
	v_lshlrev_b32_e32 v12, 16, v220
	v_add_f32_e32 v216, v216, v219
	v_and_b32_e32 v220, 0xffff0000, v220
	v_add_f32_e32 v216, v216, v12
	v_lshlrev_b32_e32 v14, 16, v221
	v_add_f32_e32 v216, v216, v220
	v_and_b32_e32 v221, 0xffff0000, v221
	v_add_f32_e32 v216, v216, v14
	v_lshlrev_b32_e32 v16, 16, v222
	v_add_f32_e32 v216, v216, v221
	v_and_b32_e32 v222, 0xffff0000, v222
	v_add_f32_e32 v216, v216, v16
	v_lshlrev_b32_e32 v18, 16, v223
	v_add_f32_e32 v216, v216, v222
	v_and_b32_e32 v223, 0xffff0000, v223
	v_add_f32_e32 v216, v216, v18
	v_add_f32_e32 v216, v216, v223
	ds_swizzle_b32 v19, v216 offset:swizzle(SWAP,16)
	s_waitcnt lgkmcnt(0)
	v_add_f32_e32 v216, v216, v19
	ds_swizzle_b32 v19, v216 offset:swizzle(SWAP,8)
	s_waitcnt lgkmcnt(0)
	v_add_f32_e32 v216, v216, v19
	ds_swizzle_b32 v19, v216 offset:swizzle(SWAP,4)
	s_waitcnt lgkmcnt(0)
	v_add_f32_e32 v216, v216, v19
	ds_swizzle_b32 v19, v216 offset:swizzle(SWAP,2)
	s_waitcnt lgkmcnt(0)
	v_add_f32_e32 v216, v216, v19
	ds_swizzle_b32 v19, v216 offset:swizzle(SWAP,1)
	s_waitcnt lgkmcnt(0)
	v_add_f32_e32 v216, v216, v19
	v_mov_b32_e32 v19, v216
	s_nop 1
	v_permlane32_swap_b32_e32 v216, v19
	v_add_f32_e32 v216, v216, v19
	v_fmac_f32_e32 v11, 0xba800000, v216
	v_fmac_f32_e32 v10, 0xba800000, v216
	v_mul_f32_e32 v11, v11, v11
	v_fmac_f32_e32 v13, 0xba800000, v216
	v_fmac_f32_e32 v11, v10, v10
	v_fmac_f32_e32 v217, 0xba800000, v216
	v_fmac_f32_e32 v11, v13, v13
	v_fmac_f32_e32 v15, 0xba800000, v216
	v_fmac_f32_e32 v11, v217, v217
	v_fmac_f32_e32 v218, 0xba800000, v216
	v_fmac_f32_e32 v11, v15, v15
	v_fmac_f32_e32 v17, 0xba800000, v216
	v_fmac_f32_e32 v11, v218, v218
	v_fmac_f32_e32 v219, 0xba800000, v216
	v_fmac_f32_e32 v11, v17, v17
	v_fmac_f32_e32 v12, 0xba800000, v216
	v_fmac_f32_e32 v11, v219, v219
	v_fmac_f32_e32 v220, 0xba800000, v216
	v_fmac_f32_e32 v11, v12, v12
	v_fmac_f32_e32 v14, 0xba800000, v216
	v_fmac_f32_e32 v11, v220, v220
	v_fmac_f32_e32 v221, 0xba800000, v216
	v_fmac_f32_e32 v11, v14, v14
	v_fmac_f32_e32 v16, 0xba800000, v216
	v_fmac_f32_e32 v11, v221, v221
	v_fmac_f32_e32 v222, 0xba800000, v216
	v_fmac_f32_e32 v11, v16, v16
	v_fmac_f32_e32 v18, 0xba800000, v216
	v_fmac_f32_e32 v11, v222, v222
	v_fmac_f32_e32 v223, 0xba800000, v216
	v_fmac_f32_e32 v11, v18, v18
	v_fmac_f32_e32 v11, v223, v223
	ds_swizzle_b32 v217, v11 offset:swizzle(SWAP,16)
	s_waitcnt lgkmcnt(0)
	v_add_f32_e32 v217, v11, v217
	ds_swizzle_b32 v218, v217 offset:swizzle(SWAP,8)
	s_waitcnt lgkmcnt(0)
	v_add_f32_e32 v217, v217, v218
	ds_swizzle_b32 v218, v217 offset:swizzle(SWAP,4)
	s_waitcnt lgkmcnt(0)
	v_add_f32_e32 v217, v217, v218
	ds_swizzle_b32 v218, v217 offset:swizzle(SWAP,2)
	s_waitcnt lgkmcnt(0)
	v_add_f32_e32 v217, v217, v218
	ds_swizzle_b32 v218, v217 offset:swizzle(SWAP,1)
	s_waitcnt lgkmcnt(0)
	v_add_f32_e32 v217, v217, v218
	v_mov_b32_e32 v218, v217
	s_nop 1
	v_permlane32_swap_b32_e32 v217, v218
	s_and_saveexec_b64 s[6:7], vcc
	s_cbranch_execz .Lln_skip_2
	v_add_f32_e32 v217, v217, v218
	v_fmamk_f32 v217, v217, 0x3a800000, v169
	v_mul_f32_e32 v218, 0x4b800000, v217
	v_cmp_gt_f32_e64 s[40:41], s85, v217
	v_mul_f32_e32 v216, 0x3a800000, v216
	s_nop 0
	v_cndmask_b32_e64 v217, v217, v218, s[40:41]
	v_rsq_f32_e32 v217, v217
	v_add_u32_e32 v218, s0, v33
	v_add_u32_e32 v219, 0x11000, v218
	ds_write_b32 v219, v216
	v_mul_f32_e32 v216, 0x45800000, v217
	v_cndmask_b32_e64 v216, v217, v216, s[40:41]
	v_add_u32_e32 v217, 0x11200, v218
	ds_write_b32 v217, v216
.Lln_skip_2:
	s_or_b64 exec, exec, s[6:7]
	s_add_i32 s0, s0, 4
	s_waitcnt vmcnt(1)
	v_lshlrev_b32_e32 v10, 16, v224
	v_and_b32_e32 v11, 0xffff0000, v224
	v_add_f32_e32 v224, 0, v10
	v_lshlrev_b32_e32 v13, 16, v225
	v_add_f32_e32 v224, v224, v11
	v_and_b32_e32 v225, 0xffff0000, v225
	v_add_f32_e32 v224, v224, v13
	v_lshlrev_b32_e32 v15, 16, v226
	v_add_f32_e32 v224, v224, v225
	v_and_b32_e32 v226, 0xffff0000, v226
	v_add_f32_e32 v224, v224, v15
	v_lshlrev_b32_e32 v17, 16, v227
	v_add_f32_e32 v224, v224, v226
	v_and_b32_e32 v227, 0xffff0000, v227
	v_add_f32_e32 v224, v224, v17
	s_waitcnt vmcnt(0)
	v_lshlrev_b32_e32 v12, 16, v228
	v_add_f32_e32 v224, v224, v227
	v_and_b32_e32 v228, 0xffff0000, v228
	v_add_f32_e32 v224, v224, v12
	v_lshlrev_b32_e32 v14, 16, v229
	v_add_f32_e32 v224, v224, v228
	v_and_b32_e32 v229, 0xffff0000, v229
	v_add_f32_e32 v224, v224, v14
	v_lshlrev_b32_e32 v16, 16, v230
	v_add_f32_e32 v224, v224, v229
	v_and_b32_e32 v230, 0xffff0000, v230
	v_add_f32_e32 v224, v224, v16
	v_lshlrev_b32_e32 v18, 16, v231
	v_add_f32_e32 v224, v224, v230
	v_and_b32_e32 v231, 0xffff0000, v231
	v_add_f32_e32 v224, v224, v18
	v_add_f32_e32 v224, v224, v231
	ds_swizzle_b32 v19, v224 offset:swizzle(SWAP,16)
	s_waitcnt lgkmcnt(0)
	v_add_f32_e32 v224, v224, v19
	ds_swizzle_b32 v19, v224 offset:swizzle(SWAP,8)
	s_waitcnt lgkmcnt(0)
	v_add_f32_e32 v224, v224, v19
	ds_swizzle_b32 v19, v224 offset:swizzle(SWAP,4)
	s_waitcnt lgkmcnt(0)
	v_add_f32_e32 v224, v224, v19
	ds_swizzle_b32 v19, v224 offset:swizzle(SWAP,2)
	s_waitcnt lgkmcnt(0)
	v_add_f32_e32 v224, v224, v19
	ds_swizzle_b32 v19, v224 offset:swizzle(SWAP,1)
	s_waitcnt lgkmcnt(0)
	v_add_f32_e32 v224, v224, v19
	v_mov_b32_e32 v19, v224
	s_nop 1
	v_permlane32_swap_b32_e32 v224, v19
	v_add_f32_e32 v224, v224, v19
	v_fmac_f32_e32 v11, 0xba800000, v224
	v_fmac_f32_e32 v10, 0xba800000, v224
	v_mul_f32_e32 v11, v11, v11
	v_fmac_f32_e32 v13, 0xba800000, v224
	v_fmac_f32_e32 v11, v10, v10
	v_fmac_f32_e32 v225, 0xba800000, v224
	v_fmac_f32_e32 v11, v13, v13
	v_fmac_f32_e32 v15, 0xba800000, v224
	v_fmac_f32_e32 v11, v225, v225
	v_fmac_f32_e32 v226, 0xba800000, v224
	v_fmac_f32_e32 v11, v15, v15
	v_fmac_f32_e32 v17, 0xba800000, v224
	v_fmac_f32_e32 v11, v226, v226
	v_fmac_f32_e32 v227, 0xba800000, v224
	v_fmac_f32_e32 v11, v17, v17
	v_fmac_f32_e32 v12, 0xba800000, v224
	v_fmac_f32_e32 v11, v227, v227
	v_fmac_f32_e32 v228, 0xba800000, v224
	v_fmac_f32_e32 v11, v12, v12
	v_fmac_f32_e32 v14, 0xba800000, v224
	v_fmac_f32_e32 v11, v228, v228
	v_fmac_f32_e32 v229, 0xba800000, v224
	v_fmac_f32_e32 v11, v14, v14
	v_fmac_f32_e32 v16, 0xba800000, v224
	v_fmac_f32_e32 v11, v229, v229
	v_fmac_f32_e32 v230, 0xba800000, v224
	v_fmac_f32_e32 v11, v16, v16
	v_fmac_f32_e32 v18, 0xba800000, v224
	v_fmac_f32_e32 v11, v230, v230
	v_fmac_f32_e32 v231, 0xba800000, v224
	v_fmac_f32_e32 v11, v18, v18
	v_fmac_f32_e32 v11, v231, v231
	ds_swizzle_b32 v225, v11 offset:swizzle(SWAP,16)
	s_waitcnt lgkmcnt(0)
	v_add_f32_e32 v225, v11, v225
	ds_swizzle_b32 v226, v225 offset:swizzle(SWAP,8)
	s_waitcnt lgkmcnt(0)
	v_add_f32_e32 v225, v225, v226
	ds_swizzle_b32 v226, v225 offset:swizzle(SWAP,4)
	s_waitcnt lgkmcnt(0)
	v_add_f32_e32 v225, v225, v226
	ds_swizzle_b32 v226, v225 offset:swizzle(SWAP,2)
	s_waitcnt lgkmcnt(0)
	v_add_f32_e32 v225, v225, v226
	ds_swizzle_b32 v226, v225 offset:swizzle(SWAP,1)
	s_waitcnt lgkmcnt(0)
	v_add_f32_e32 v225, v225, v226
	v_mov_b32_e32 v226, v225
	s_nop 1
	v_permlane32_swap_b32_e32 v225, v226
	s_and_saveexec_b64 s[6:7], vcc
	s_cbranch_execz .Lln_skip_3
	v_add_f32_e32 v225, v225, v226
	v_fmamk_f32 v225, v225, 0x3a800000, v169
	v_mul_f32_e32 v226, 0x4b800000, v225
	v_cmp_gt_f32_e64 s[40:41], s85, v225
	v_mul_f32_e32 v224, 0x3a800000, v224
	s_nop 0
	v_cndmask_b32_e64 v225, v225, v226, s[40:41]
	v_rsq_f32_e32 v225, v225
	v_add_u32_e32 v226, s0, v33
	v_add_u32_e32 v227, 0x11000, v226
	ds_write_b32 v227, v224
	v_mul_f32_e32 v224, 0x45800000, v225
	v_cndmask_b32_e64 v224, v225, v224, s[40:41]
	v_add_u32_e32 v225, 0x11200, v226
	ds_write_b32 v225, v224
.Lln_skip_3:
	s_or_b64 exec, exec, s[6:7]
	s_add_i32 s0, s0, 4
	s_mov_b64 s[6:7], 0x4000
	v_lshl_add_u64 v[0:1], v[0:1], 0, s[6:7]
	s_cmp_eq_u32 s0, 64
	s_cbranch_scc0 .Lln_batch
	s_branch .LBB0_181

.Lfin2_check:
	v_add_u32_e32 v72, s74, v0
	v_cmp_gt_i32_e32 vcc, s0, v72
	s_nop 4
	s_cbranch_vccz .LBB0_189
	v_ashrrev_i32_e32 v1, 31, v0
	v_lshlrev_b64 v[24:25], 12, v[0:1]
	v_lshl_add_u64 v[36:37], v[2:3], 0, v[24:25]
	global_load_dwordx4 v[24:27], v[36:37], off offset:16
	global_load_dwordx4 v[28:31], v[36:37], off
	global_load_dwordx4 v[32:35], v[36:37], off offset:272
	global_load_dwordx4 v[36:39], v[36:37], off offset:256
	v_ashrrev_i32_e32 v73, 31, v72
	v_lshlrev_b64 v[50:51], 12, v[72:73]
	v_lshl_add_u64 v[62:63], v[2:3], 0, v[50:51]
	global_load_dwordx4 v[50:53], v[62:63], off offset:16
	global_load_dwordx4 v[54:57], v[62:63], off
	global_load_dwordx4 v[58:61], v[62:63], off offset:272
	global_load_dwordx4 v[62:65], v[62:63], off offset:256
	s_waitcnt vmcnt(6)
	v_lshlrev_b32_e32 v40, 16, v28
	v_and_b32_e32 v28, 0xffff0000, v28
	s_waitcnt vmcnt(4)
	v_lshlrev_b32_e32 v41, 16, v36
	v_and_b32_e32 v36, 0xffff0000, v36
	v_fma_f32 v40, -v6, v41, v40
	v_fma_f32 v36, -v6, v36, v28
	v_lshlrev_b32_e32 v28, 16, v29
	v_lshlrev_b32_e32 v41, 16, v37
	v_fma_f32 v41, -v6, v41, v28
	v_and_b32_e32 v28, 0xffff0000, v29
	v_and_b32_e32 v29, 0xffff0000, v37
	v_mul_f32_e32 v44, v36, v36
	v_fma_f32 v37, -v6, v29, v28
	v_lshlrev_b32_e32 v28, 16, v30
	v_lshlrev_b32_e32 v29, 16, v38
	v_fmac_f32_e32 v44, v40, v40
	v_fma_f32 v42, -v6, v29, v28
	v_and_b32_e32 v28, 0xffff0000, v30
	v_and_b32_e32 v29, 0xffff0000, v38
	v_fmac_f32_e32 v44, v41, v41
	v_fma_f32 v38, -v6, v29, v28
	v_lshlrev_b32_e32 v28, 16, v31
	v_lshlrev_b32_e32 v29, 16, v39
	v_fmac_f32_e32 v44, v37, v37
	v_fma_f32 v43, -v6, v29, v28
	v_and_b32_e32 v28, 0xffff0000, v31
	v_and_b32_e32 v29, 0xffff0000, v39
	v_fmac_f32_e32 v44, v42, v42
	v_fma_f32 v39, -v6, v29, v28
	v_fmac_f32_e32 v44, v38, v38
	v_and_b32_e32 v28, 0xffff0000, v24
	v_lshlrev_b32_e32 v29, 16, v24
	v_and_b32_e32 v30, 0xffff0000, v32
	v_lshlrev_b32_e32 v31, 16, v32
	v_fmac_f32_e32 v44, v43, v43
	v_pk_fma_f32 v[28:29], v[6:7], v[30:31], v[28:29] neg_lo:[1,0,0] neg_hi:[1,0,0]
	v_fmac_f32_e32 v44, v39, v39
	v_pk_mul_f32 v[30:31], v[28:29], v[28:29]
	s_nop 0
	v_add_f32_e32 v24, v31, v44
	v_add_f32_e32 v32, v30, v24
	v_and_b32_e32 v24, 0xffff0000, v25
	v_lshlrev_b32_e32 v25, 16, v25
	v_and_b32_e32 v30, 0xffff0000, v33
	v_lshlrev_b32_e32 v31, 16, v33
	v_pk_fma_f32 v[30:31], v[6:7], v[30:31], v[24:25] neg_lo:[1,0,0] neg_hi:[1,0,0]
	v_lshlrev_b32_e32 v33, 16, v34
	v_pk_mul_f32 v[24:25], v[30:31], v[30:31]
	s_nop 0
	v_add_f32_e32 v25, v25, v32
	v_add_f32_e32 v44, v24, v25
	v_and_b32_e32 v24, 0xffff0000, v26
	v_lshlrev_b32_e32 v25, 16, v26
	v_and_b32_e32 v32, 0xffff0000, v34
	v_pk_fma_f32 v[32:33], v[6:7], v[32:33], v[24:25] neg_lo:[1,0,0] neg_hi:[1,0,0]
	v_and_b32_e32 v26, 0xffff0000, v35
	v_pk_mul_f32 v[24:25], v[32:33], v[32:33]
	s_nop 0
	v_add_f32_e32 v25, v25, v44
	v_add_f32_e32 v44, v24, v25
	v_and_b32_e32 v24, 0xffff0000, v27
	v_lshlrev_b32_e32 v25, 16, v27
	v_lshlrev_b32_e32 v27, 16, v35
	v_pk_fma_f32 v[34:35], v[6:7], v[26:27], v[24:25] neg_lo:[1,0,0] neg_hi:[1,0,0]
	s_nop 0
	v_pk_mul_f32 v[24:25], v[34:35], v[34:35]
	s_nop 0
	v_add_f32_e32 v25, v25, v44
	v_add_f32_e32 v24, v24, v25
	ds_swizzle_b32 v25, v24 offset:swizzle(SWAP,1)
	s_waitcnt lgkmcnt(0)
	v_add_f32_e32 v24, v24, v25
	ds_swizzle_b32 v25, v24 offset:swizzle(SWAP,2)
	s_waitcnt lgkmcnt(0)
	v_add_f32_e32 v24, v24, v25
	ds_swizzle_b32 v25, v24 offset:swizzle(SWAP,4)
	s_waitcnt lgkmcnt(0)
	v_add_f32_e32 v24, v24, v25
	v_fmamk_f32 v24, v24, 0x3c000000, v169
	v_cmp_gt_f32_e32 vcc, s85, v24
	v_mul_f32_e32 v25, 0x4b800000, v24
	s_nop 0
	v_cndmask_b32_e32 v24, v24, v25, vcc
	v_rsq_f32_e32 v24, v24
	s_nop 0
	v_mul_f32_e32 v25, 0x45800000, v24
	v_cndmask_b32_e32 v44, v24, v25, vcc
	v_mul_f32_e32 v24, v40, v44
	v_mul_f32_e32 v25, v36, v44
	v_mul_f32_e32 v24, v8, v24
	v_mul_f32_e32 v25, v9, v25
	v_cvt_pk_bf16_f32 v24, v24, v25
	v_mul_f32_e32 v25, v29, v44
	v_mul_f32_e32 v26, v28, v44
	v_mul_f32_e32 v25, v16, v25
	v_mul_f32_e32 v26, v17, v26
	v_cvt_pk_bf16_f32 v28, v25, v26
	v_mul_f32_e32 v25, v41, v44
	v_mul_f32_e32 v26, v37, v44
	v_mul_f32_e32 v25, v10, v25
	v_mul_f32_e32 v26, v11, v26
	v_cvt_pk_bf16_f32 v25, v25, v26
	v_mul_f32_e32 v26, v31, v44
	v_mul_f32_e32 v27, v30, v44
	v_mul_f32_e32 v26, v18, v26
	v_mul_f32_e32 v27, v19, v27
	v_cvt_pk_bf16_f32 v29, v26, v27
	v_mul_f32_e32 v26, v42, v44
	v_mul_f32_e32 v27, v38, v44
	v_mul_f32_e32 v26, v12, v26
	v_mul_f32_e32 v27, v13, v27
	v_cvt_pk_bf16_f32 v26, v26, v27
	v_mul_f32_e32 v27, v33, v44
	v_mul_f32_e32 v30, v32, v44
	v_mul_f32_e32 v27, v20, v27
	v_mul_f32_e32 v30, v21, v30
	v_cvt_pk_bf16_f32 v30, v27, v30
	v_mul_f32_e32 v27, v43, v44
	v_mul_f32_e32 v31, v39, v44
	v_mul_f32_e32 v27, v14, v27
	v_mul_f32_e32 v31, v15, v31
	v_cvt_pk_bf16_f32 v27, v27, v31
	v_mul_f32_e32 v31, v35, v44
	v_mul_f32_e32 v32, v34, v44
	v_mul_f32_e32 v31, v22, v31
	v_mul_f32_e32 v32, v23, v32
	v_cvt_pk_bf16_f32 v31, v31, v32
	v_lshlrev_b64 v[32:33], 11, v[0:1]
	v_lshl_add_u64 v[32:33], v[4:5], 0, v[32:33]
	s_waitcnt vmcnt(2)
	v_lshlrev_b32_e32 v66, 16, v54
	v_and_b32_e32 v54, 0xffff0000, v54
	s_waitcnt vmcnt(0)
	v_lshlrev_b32_e32 v67, 16, v62
	v_and_b32_e32 v62, 0xffff0000, v62
	v_fma_f32 v66, -v6, v67, v66
	v_fma_f32 v62, -v6, v62, v54
	v_lshlrev_b32_e32 v54, 16, v55
	v_lshlrev_b32_e32 v67, 16, v63
	v_fma_f32 v67, -v6, v67, v54
	v_and_b32_e32 v54, 0xffff0000, v55
	v_and_b32_e32 v55, 0xffff0000, v63
	v_mul_f32_e32 v70, v62, v62
	v_fma_f32 v63, -v6, v55, v54
	v_lshlrev_b32_e32 v54, 16, v56
	v_lshlrev_b32_e32 v55, 16, v64
	v_fmac_f32_e32 v70, v66, v66
	v_fma_f32 v68, -v6, v55, v54
	v_and_b32_e32 v54, 0xffff0000, v56
	v_and_b32_e32 v55, 0xffff0000, v64
	v_fmac_f32_e32 v70, v67, v67
	v_fma_f32 v64, -v6, v55, v54
	v_lshlrev_b32_e32 v54, 16, v57
	v_lshlrev_b32_e32 v55, 16, v65
	v_fmac_f32_e32 v70, v63, v63
	v_fma_f32 v69, -v6, v55, v54
	v_and_b32_e32 v54, 0xffff0000, v57
	v_and_b32_e32 v55, 0xffff0000, v65
	v_fmac_f32_e32 v70, v68, v68
	v_fma_f32 v65, -v6, v55, v54
	v_fmac_f32_e32 v70, v64, v64
	v_and_b32_e32 v54, 0xffff0000, v50
	v_lshlrev_b32_e32 v55, 16, v50
	v_and_b32_e32 v56, 0xffff0000, v58
	v_lshlrev_b32_e32 v57, 16, v58
	v_fmac_f32_e32 v70, v69, v69
	v_pk_fma_f32 v[54:55], v[6:7], v[56:57], v[54:55] neg_lo:[1,0,0] neg_hi:[1,0,0]
	v_fmac_f32_e32 v70, v65, v65
	v_pk_mul_f32 v[56:57], v[54:55], v[54:55]
	s_nop 0
	v_add_f32_e32 v50, v57, v70
	v_add_f32_e32 v58, v56, v50
	v_and_b32_e32 v50, 0xffff0000, v51
	v_lshlrev_b32_e32 v51, 16, v51
	v_and_b32_e32 v56, 0xffff0000, v59
	v_lshlrev_b32_e32 v57, 16, v59
	v_pk_fma_f32 v[56:57], v[6:7], v[56:57], v[50:51] neg_lo:[1,0,0] neg_hi:[1,0,0]
	v_lshlrev_b32_e32 v59, 16, v60
	v_pk_mul_f32 v[50:51], v[56:57], v[56:57]
	s_nop 0
	v_add_f32_e32 v51, v51, v58
	v_add_f32_e32 v70, v50, v51
	v_and_b32_e32 v50, 0xffff0000, v52
	v_lshlrev_b32_e32 v51, 16, v52
	v_and_b32_e32 v58, 0xffff0000, v60
	v_pk_fma_f32 v[58:59], v[6:7], v[58:59], v[50:51] neg_lo:[1,0,0] neg_hi:[1,0,0]
	v_and_b32_e32 v52, 0xffff0000, v61
	v_pk_mul_f32 v[50:51], v[58:59], v[58:59]
	s_nop 0
	v_add_f32_e32 v51, v51, v70
	v_add_f32_e32 v70, v50, v51
	v_and_b32_e32 v50, 0xffff0000, v53
	v_lshlrev_b32_e32 v51, 16, v53
	v_lshlrev_b32_e32 v53, 16, v61
	v_pk_fma_f32 v[60:61], v[6:7], v[52:53], v[50:51] neg_lo:[1,0,0] neg_hi:[1,0,0]
	s_nop 0
	v_pk_mul_f32 v[50:51], v[60:61], v[60:61]
	s_nop 0
	v_add_f32_e32 v51, v51, v70
	v_add_f32_e32 v50, v50, v51
	ds_swizzle_b32 v51, v50 offset:swizzle(SWAP,1)
	s_waitcnt lgkmcnt(0)
	v_add_f32_e32 v50, v50, v51
	ds_swizzle_b32 v51, v50 offset:swizzle(SWAP,2)
	s_waitcnt lgkmcnt(0)
	v_add_f32_e32 v50, v50, v51
	ds_swizzle_b32 v51, v50 offset:swizzle(SWAP,4)
	s_waitcnt lgkmcnt(0)
	v_add_f32_e32 v50, v50, v51
	v_fmamk_f32 v50, v50, 0x3c000000, v169
	v_cmp_gt_f32_e32 vcc, s85, v50
	v_mul_f32_e32 v51, 0x4b800000, v50
	s_nop 0
	v_cndmask_b32_e32 v50, v50, v51, vcc
	v_rsq_f32_e32 v50, v50
	s_nop 0
	v_mul_f32_e32 v51, 0x45800000, v50
	v_cndmask_b32_e32 v70, v50, v51, vcc
	v_mul_f32_e32 v50, v66, v70
	v_mul_f32_e32 v51, v62, v70
	v_mul_f32_e32 v50, v8, v50
	v_mul_f32_e32 v51, v9, v51
	v_cvt_pk_bf16_f32 v50, v50, v51
	v_mul_f32_e32 v51, v55, v70
	v_mul_f32_e32 v52, v54, v70
	v_mul_f32_e32 v51, v16, v51
	v_mul_f32_e32 v52, v17, v52
	v_cvt_pk_bf16_f32 v54, v51, v52
	v_mul_f32_e32 v51, v67, v70
	v_mul_f32_e32 v52, v63, v70
	v_mul_f32_e32 v51, v10, v51
	v_mul_f32_e32 v52, v11, v52
	v_cvt_pk_bf16_f32 v51, v51, v52
	v_mul_f32_e32 v52, v57, v70
	v_mul_f32_e32 v53, v56, v70
	v_mul_f32_e32 v52, v18, v52
	v_mul_f32_e32 v53, v19, v53
	v_cvt_pk_bf16_f32 v55, v52, v53
	v_mul_f32_e32 v52, v68, v70
	v_mul_f32_e32 v53, v64, v70
	v_mul_f32_e32 v52, v12, v52
	v_mul_f32_e32 v53, v13, v53
	v_cvt_pk_bf16_f32 v52, v52, v53
	v_mul_f32_e32 v53, v59, v70
	v_mul_f32_e32 v56, v58, v70
	v_mul_f32_e32 v53, v20, v53
	v_mul_f32_e32 v56, v21, v56
	v_cvt_pk_bf16_f32 v56, v53, v56
	v_mul_f32_e32 v53, v69, v70
	v_mul_f32_e32 v57, v65, v70
	v_mul_f32_e32 v53, v14, v53
	v_mul_f32_e32 v57, v15, v57
	v_cvt_pk_bf16_f32 v53, v53, v57
	v_mul_f32_e32 v57, v61, v70
	v_mul_f32_e32 v58, v60, v70
	v_mul_f32_e32 v57, v22, v57
	v_mul_f32_e32 v58, v23, v58
	v_cvt_pk_bf16_f32 v57, v57, v58
	v_lshlrev_b64 v[58:59], 11, v[72:73]
	v_lshl_add_u64 v[58:59], v[4:5], 0, v[58:59]
	global_store_dwordx4 v[58:59], v[50:53], off
	global_store_dwordx4 v[58:59], v[54:57], off offset:16
	global_store_dwordx4 v[32:33], v[24:27], off
	global_store_dwordx4 v[32:33], v[28:31], off offset:16
	v_add_u32_e32 v0, s74, v72
	v_cmp_gt_i32_e32 vcc, s0, v0
	s_nop 4
	s_cbranch_vccnz .Lfin2_check
	s_branch .LBB0_190
	s_nop 0
	s_nop 0
	s_nop 0
	s_nop 0
	s_nop 0
	s_nop 0
	s_nop 0
	s_nop 0
	s_nop 0
	s_nop 0
	s_nop 0
	s_nop 0
	s_nop 0
	s_nop 0
	s_nop 0
	s_nop 0
	s_nop 0
	s_nop 0
	s_nop 0
	s_nop 0
	s_nop 0
	s_nop 0
	s_nop 0
